# v50 + lean barrier: acquire invalidate moved off the XCD-last leader's critical chain (after the TOP atomic / after the arrival wait)
# speedup vs baseline: 1.0030x; 1.0030x over previous
.LBB0_233:
	s_cmp_gt_i32 s59, 2
	s_cselect_b64 s[6:7], -1, 0
	s_and_b64 s[0:1], s[0:1], s[6:7]
	s_andn2_b64 vcc, exec, s[0:1]
	s_cbranch_vccnz .LBB0_287
	s_waitcnt vmcnt(0) lgkmcnt(0)
	s_barrier
	s_mov_b64 s[0:1], exec
	v_readlane_b32 s2, v249, 5
	v_readlane_b32 s3, v249, 6
	v_readlane_b32 s8, v249, 4
	s_and_b64 s[2:3], s[0:1], s[2:3]
	s_mov_b64 exec, s[2:3]
	s_cbranch_execz .Lgb_1_done
	v_mov_b32_e32 v1, 0x27e00
	ds_read2_b32 v[2:3], v1 offset1:1
	s_lshl_b32 s8, s8, 8
	s_add_u32 s4, s56, s8
	s_addc_u32 s5, s57, 0
	v_mov_b32_e32 v4, 0x1000
	v_mov_b32_e32 v5, 1
	global_atomic_add v6, v4, v5, s[4:5] offset:1024 sc0
	s_waitcnt lgkmcnt(0)
	v_mul_lo_u32 v7, v2, 2
	s_waitcnt vmcnt(0)
	v_add_u32_e32 v6, 1, v6
	v_cmp_eq_u32_e32 vcc, v6, v7
	s_cbranch_vccz .Lgb_1_waiti
	buffer_wbl2 sc1
	s_waitcnt vmcnt(0)
	v_mov_b32_e32 v4, 0x3000
	global_atomic_add v8, v4, v5, s[56:57] offset:1024 sc0
	buffer_inv sc1
	v_mul_lo_u32 v7, v3, 2
	s_waitcnt vmcnt(1)
	v_add_u32_e32 v8, 1, v8
	v_cmp_eq_u32_e32 vcc, v8, v7
	s_cbranch_vccz .Lgb_1_wait
	v_mov_b32_e32 v9, 0x2400
	global_atomic_add v9, v5, s[56:57] offset:0
	global_atomic_add v9, v5, s[56:57] offset:256
	global_atomic_add v9, v5, s[56:57] offset:512
	global_atomic_add v9, v5, s[56:57] offset:768
	global_atomic_add v9, v5, s[56:57] offset:1024
	global_atomic_add v9, v5, s[56:57] offset:1280
	global_atomic_add v9, v5, s[56:57] offset:1536
	global_atomic_add v9, v5, s[56:57] offset:1792
	global_atomic_add v9, v5, s[56:57] offset:2048
	global_atomic_add v9, v5, s[56:57] offset:2304
	global_atomic_add v9, v5, s[56:57] offset:2560
	global_atomic_add v9, v5, s[56:57] offset:2816
	global_atomic_add v9, v5, s[56:57] offset:3072
	global_atomic_add v9, v5, s[56:57] offset:3328
	global_atomic_add v9, v5, s[56:57] offset:3584
	global_atomic_add v9, v5, s[56:57] offset:3840
	s_waitcnt vmcnt(0)
	s_branch .Lgb_1_done
.Lgb_1_waiti:
	buffer_inv sc1

.LBB0_320:
	s_cmp_gt_i32 s59, 3
	s_cselect_b64 s[6:7], -1, 0
	s_and_b64 s[2:3], s[4:5], s[6:7]
	s_andn2_b64 vcc, exec, s[2:3]
	s_cbranch_vccnz .LBB0_374
	s_waitcnt vmcnt(0) lgkmcnt(0)
	s_barrier
	s_mov_b64 s[2:3], exec
	v_readlane_b32 s4, v249, 5
	v_readlane_b32 s5, v249, 6
	v_readlane_b32 s10, v249, 4
	s_and_b64 s[4:5], s[2:3], s[4:5]
	s_mov_b64 exec, s[4:5]
	s_cbranch_execz .Lgb_2_done
	v_mov_b32_e32 v1, 0x27e00
	ds_read2_b32 v[2:3], v1 offset1:1
	s_lshl_b32 s10, s10, 8
	s_add_u32 s8, s56, s10
	s_addc_u32 s9, s57, 0
	v_mov_b32_e32 v4, 0x1000
	v_mov_b32_e32 v5, 1
	global_atomic_add v6, v4, v5, s[8:9] offset:1024 sc0
	s_waitcnt lgkmcnt(0)
	v_mul_lo_u32 v7, v2, 3
	s_waitcnt vmcnt(0)
	v_add_u32_e32 v6, 1, v6
	v_cmp_eq_u32_e32 vcc, v6, v7
	s_cbranch_vccz .Lgb_2_waiti
	buffer_wbl2 sc1
	s_waitcnt vmcnt(0)
	v_mov_b32_e32 v4, 0x3000
	global_atomic_add v8, v4, v5, s[56:57] offset:1024 sc0
	buffer_inv sc1
	v_mul_lo_u32 v7, v3, 3
	s_waitcnt vmcnt(1)
	v_add_u32_e32 v8, 1, v8
	v_cmp_eq_u32_e32 vcc, v8, v7
	s_cbranch_vccz .Lgb_2_wait
	v_mov_b32_e32 v9, 0x2400
	global_atomic_add v9, v5, s[56:57] offset:0
	global_atomic_add v9, v5, s[56:57] offset:256
	global_atomic_add v9, v5, s[56:57] offset:512
	global_atomic_add v9, v5, s[56:57] offset:768
	global_atomic_add v9, v5, s[56:57] offset:1024
	global_atomic_add v9, v5, s[56:57] offset:1280
	global_atomic_add v9, v5, s[56:57] offset:1536
	global_atomic_add v9, v5, s[56:57] offset:1792
	global_atomic_add v9, v5, s[56:57] offset:2048
	global_atomic_add v9, v5, s[56:57] offset:2304
	global_atomic_add v9, v5, s[56:57] offset:2560
	global_atomic_add v9, v5, s[56:57] offset:2816
	global_atomic_add v9, v5, s[56:57] offset:3072
	global_atomic_add v9, v5, s[56:57] offset:3328
	global_atomic_add v9, v5, s[56:57] offset:3584
	global_atomic_add v9, v5, s[56:57] offset:3840
	s_waitcnt vmcnt(0)
	s_branch .Lgb_2_done

.LBB0_413:
	s_cmp_gt_i32 s59, 4
	s_cselect_b64 s[6:7], -1, 0
	s_and_b64 s[2:3], s[4:5], s[6:7]
	s_andn2_b64 vcc, exec, s[2:3]
	s_cbranch_vccnz .LBB0_467
	s_waitcnt vmcnt(0) lgkmcnt(0)
	s_barrier
	s_mov_b64 s[2:3], exec
	v_readlane_b32 s4, v249, 5
	v_readlane_b32 s5, v249, 6
	v_readlane_b32 s10, v249, 4
	s_and_b64 s[4:5], s[2:3], s[4:5]
	s_mov_b64 exec, s[4:5]
	s_cbranch_execz .Lgb_3_done
	v_mov_b32_e32 v1, 0x27e00
	ds_read2_b32 v[2:3], v1 offset1:1
	s_lshl_b32 s10, s10, 8
	s_add_u32 s8, s56, s10
	s_addc_u32 s9, s57, 0
	v_mov_b32_e32 v4, 0x1000
	v_mov_b32_e32 v5, 1
	global_atomic_add v6, v4, v5, s[8:9] offset:1024 sc0
	s_waitcnt lgkmcnt(0)
	v_mul_lo_u32 v7, v2, 4
	s_waitcnt vmcnt(0)
	v_add_u32_e32 v6, 1, v6
	v_cmp_eq_u32_e32 vcc, v6, v7
	s_cbranch_vccz .Lgb_3_waiti
	buffer_wbl2 sc1
	s_waitcnt vmcnt(0)
	v_mov_b32_e32 v4, 0x3000
	global_atomic_add v8, v4, v5, s[56:57] offset:1024 sc0
	buffer_inv sc1
	v_mul_lo_u32 v7, v3, 4
	s_waitcnt vmcnt(1)
	v_add_u32_e32 v8, 1, v8
	v_cmp_eq_u32_e32 vcc, v8, v7
	s_cbranch_vccz .Lgb_3_wait
	v_mov_b32_e32 v9, 0x2400
	global_atomic_add v9, v5, s[56:57] offset:0
	global_atomic_add v9, v5, s[56:57] offset:256
	global_atomic_add v9, v5, s[56:57] offset:512
	global_atomic_add v9, v5, s[56:57] offset:768
	global_atomic_add v9, v5, s[56:57] offset:1024
	global_atomic_add v9, v5, s[56:57] offset:1280
	global_atomic_add v9, v5, s[56:57] offset:1536
	global_atomic_add v9, v5, s[56:57] offset:1792
	global_atomic_add v9, v5, s[56:57] offset:2048
	global_atomic_add v9, v5, s[56:57] offset:2304
	global_atomic_add v9, v5, s[56:57] offset:2560
	global_atomic_add v9, v5, s[56:57] offset:2816
	global_atomic_add v9, v5, s[56:57] offset:3072
	global_atomic_add v9, v5, s[56:57] offset:3328
	global_atomic_add v9, v5, s[56:57] offset:3584
	global_atomic_add v9, v5, s[56:57] offset:3840
	s_waitcnt vmcnt(0)
	s_branch .Lgb_3_done

.LBB0_484:
	s_cmp_gt_i32 s59, 5
	s_cselect_b64 s[6:7], -1, 0
	s_and_b64 s[2:3], s[4:5], s[6:7]
	s_andn2_b64 vcc, exec, s[2:3]
	s_cbranch_vccnz .LBB0_538
	s_waitcnt vmcnt(0) lgkmcnt(0)
	s_barrier
	s_mov_b64 s[2:3], exec
	v_readlane_b32 s4, v249, 5
	v_readlane_b32 s5, v249, 6
	v_readlane_b32 s10, v249, 4
	s_and_b64 s[4:5], s[2:3], s[4:5]
	s_mov_b64 exec, s[4:5]
	s_cbranch_execz .Lgb_4_done
	v_mov_b32_e32 v1, 0x27e00
	ds_read2_b32 v[2:3], v1 offset1:1
	s_lshl_b32 s10, s10, 8
	s_add_u32 s8, s56, s10
	s_addc_u32 s9, s57, 0
	v_mov_b32_e32 v4, 0x1000
	v_mov_b32_e32 v5, 1
	global_atomic_add v6, v4, v5, s[8:9] offset:1024 sc0
	s_waitcnt lgkmcnt(0)
	v_mul_lo_u32 v7, v2, 5
	s_waitcnt vmcnt(0)
	v_add_u32_e32 v6, 1, v6
	v_cmp_eq_u32_e32 vcc, v6, v7
	s_cbranch_vccz .Lgb_4_waiti
	buffer_wbl2 sc1
	s_waitcnt vmcnt(0)
	v_mov_b32_e32 v4, 0x3000
	global_atomic_add v8, v4, v5, s[56:57] offset:1024 sc0
	buffer_inv sc1
	v_mul_lo_u32 v7, v3, 5
	s_waitcnt vmcnt(1)
	v_add_u32_e32 v8, 1, v8
	v_cmp_eq_u32_e32 vcc, v8, v7
	s_cbranch_vccz .Lgb_4_wait
	v_mov_b32_e32 v9, 0x2400
	global_atomic_add v9, v5, s[56:57] offset:0
	global_atomic_add v9, v5, s[56:57] offset:256
	global_atomic_add v9, v5, s[56:57] offset:512
	global_atomic_add v9, v5, s[56:57] offset:768
	global_atomic_add v9, v5, s[56:57] offset:1024
	global_atomic_add v9, v5, s[56:57] offset:1280
	global_atomic_add v9, v5, s[56:57] offset:1536
	global_atomic_add v9, v5, s[56:57] offset:1792
	global_atomic_add v9, v5, s[56:57] offset:2048
	global_atomic_add v9, v5, s[56:57] offset:2304
	global_atomic_add v9, v5, s[56:57] offset:2560
	global_atomic_add v9, v5, s[56:57] offset:2816
	global_atomic_add v9, v5, s[56:57] offset:3072
	global_atomic_add v9, v5, s[56:57] offset:3328
	global_atomic_add v9, v5, s[56:57] offset:3584
	global_atomic_add v9, v5, s[56:57] offset:3840
	s_waitcnt vmcnt(0)
	s_branch .Lgb_4_done

.LBB0_681:
	s_cmp_gt_i32 s59, 7
	s_cselect_b64 s[4:5], -1, 0
	s_and_b64 s[2:3], s[10:11], s[4:5]
	s_andn2_b64 vcc, exec, s[2:3]
	s_cbranch_vccnz .LBB0_735
	s_waitcnt vmcnt(0) lgkmcnt(0)
	s_barrier
	s_mov_b64 s[2:3], exec
	v_readlane_b32 s6, v249, 5
	v_readlane_b32 s7, v249, 6
	v_readlane_b32 s10, v249, 4
	s_and_b64 s[6:7], s[2:3], s[6:7]
	s_mov_b64 exec, s[6:7]
	s_cbranch_execz .Lgb_5_done
	v_mov_b32_e32 v1, 0x27e00
	ds_read2_b32 v[2:3], v1 offset1:1
	s_lshl_b32 s10, s10, 8
	s_add_u32 s8, s56, s10
	s_addc_u32 s9, s57, 0
	v_mov_b32_e32 v4, 0x1000
	v_mov_b32_e32 v5, 1
	global_atomic_add v6, v4, v5, s[8:9] offset:1024 sc0
	s_waitcnt lgkmcnt(0)
	v_mul_lo_u32 v7, v2, 6
	s_waitcnt vmcnt(0)
	v_add_u32_e32 v6, 1, v6
	v_cmp_eq_u32_e32 vcc, v6, v7
	s_cbranch_vccz .Lgb_5_waiti
	buffer_wbl2 sc1
	s_waitcnt vmcnt(0)
	v_mov_b32_e32 v4, 0x3000
	global_atomic_add v8, v4, v5, s[56:57] offset:1024 sc0
	buffer_inv sc1
	v_mul_lo_u32 v7, v3, 6
	s_waitcnt vmcnt(1)
	v_add_u32_e32 v8, 1, v8
	v_cmp_eq_u32_e32 vcc, v8, v7
	s_cbranch_vccz .Lgb_5_wait
	v_mov_b32_e32 v9, 0x2400
	global_atomic_add v9, v5, s[56:57] offset:0
	global_atomic_add v9, v5, s[56:57] offset:256
	global_atomic_add v9, v5, s[56:57] offset:512
	global_atomic_add v9, v5, s[56:57] offset:768
	global_atomic_add v9, v5, s[56:57] offset:1024
	global_atomic_add v9, v5, s[56:57] offset:1280
	global_atomic_add v9, v5, s[56:57] offset:1536
	global_atomic_add v9, v5, s[56:57] offset:1792
	global_atomic_add v9, v5, s[56:57] offset:2048
	global_atomic_add v9, v5, s[56:57] offset:2304
	global_atomic_add v9, v5, s[56:57] offset:2560
	global_atomic_add v9, v5, s[56:57] offset:2816
	global_atomic_add v9, v5, s[56:57] offset:3072
	global_atomic_add v9, v5, s[56:57] offset:3328
	global_atomic_add v9, v5, s[56:57] offset:3584
	global_atomic_add v9, v5, s[56:57] offset:3840
	s_waitcnt vmcnt(0)
	s_branch .Lgb_5_done

.LBB0_752:
	s_cmp_gt_i32 s59, 8
	s_cselect_b64 s[4:5], -1, 0
	s_and_b64 s[2:3], s[6:7], s[4:5]
	s_andn2_b64 vcc, exec, s[2:3]
	s_cbranch_vccnz .LBB0_806
	s_waitcnt vmcnt(0) lgkmcnt(0)
	s_barrier
	s_mov_b64 s[2:3], exec
	v_readlane_b32 s6, v249, 5
	v_readlane_b32 s7, v249, 6
	v_readlane_b32 s10, v249, 4
	s_and_b64 s[6:7], s[2:3], s[6:7]
	s_mov_b64 exec, s[6:7]
	s_cbranch_execz .Lgb_6_done
	v_mov_b32_e32 v1, 0x27e00
	ds_read2_b32 v[2:3], v1 offset1:1
	s_lshl_b32 s10, s10, 8
	s_add_u32 s8, s56, s10
	s_addc_u32 s9, s57, 0
	v_mov_b32_e32 v4, 0x1000
	v_mov_b32_e32 v5, 1
	global_atomic_add v6, v4, v5, s[8:9] offset:1024 sc0
	s_waitcnt lgkmcnt(0)
	v_mul_lo_u32 v7, v2, 7
	s_waitcnt vmcnt(0)
	v_add_u32_e32 v6, 1, v6
	v_cmp_eq_u32_e32 vcc, v6, v7
	s_cbranch_vccz .Lgb_6_waiti
	buffer_wbl2 sc1
	s_waitcnt vmcnt(0)
	v_mov_b32_e32 v4, 0x3000
	global_atomic_add v8, v4, v5, s[56:57] offset:1024 sc0
	buffer_inv sc1
	v_mul_lo_u32 v7, v3, 7
	s_waitcnt vmcnt(1)
	v_add_u32_e32 v8, 1, v8
	v_cmp_eq_u32_e32 vcc, v8, v7
	s_cbranch_vccz .Lgb_6_wait
	v_mov_b32_e32 v9, 0x2400
	global_atomic_add v9, v5, s[56:57] offset:0
	global_atomic_add v9, v5, s[56:57] offset:256
	global_atomic_add v9, v5, s[56:57] offset:512
	global_atomic_add v9, v5, s[56:57] offset:768
	global_atomic_add v9, v5, s[56:57] offset:1024
	global_atomic_add v9, v5, s[56:57] offset:1280
	global_atomic_add v9, v5, s[56:57] offset:1536
	global_atomic_add v9, v5, s[56:57] offset:1792
	global_atomic_add v9, v5, s[56:57] offset:2048
	global_atomic_add v9, v5, s[56:57] offset:2304
	global_atomic_add v9, v5, s[56:57] offset:2560
	global_atomic_add v9, v5, s[56:57] offset:2816
	global_atomic_add v9, v5, s[56:57] offset:3072
	global_atomic_add v9, v5, s[56:57] offset:3328
	global_atomic_add v9, v5, s[56:57] offset:3584
	global_atomic_add v9, v5, s[56:57] offset:3840
	s_waitcnt vmcnt(0)
	s_branch .Lgb_6_done

.LBB0_949:
	s_cmp_gt_i32 s59, 10
	s_cselect_b64 s[4:5], -1, 0
	s_and_b64 s[0:1], s[10:11], s[4:5]
	s_andn2_b64 vcc, exec, s[0:1]
	s_cbranch_vccnz .LBB0_1003
	s_waitcnt vmcnt(0) lgkmcnt(0)
	s_barrier
	s_mov_b64 s[0:1], exec
	v_readlane_b32 s2, v249, 5
	v_readlane_b32 s3, v249, 6
	v_readlane_b32 s8, v249, 4
	s_and_b64 s[2:3], s[0:1], s[2:3]
	s_mov_b64 exec, s[2:3]
	s_cbranch_execz .Lgb_7_done
	v_mov_b32_e32 v1, 0x27e00
	ds_read2_b32 v[2:3], v1 offset1:1
	s_lshl_b32 s8, s8, 8
	s_add_u32 s6, s56, s8
	s_addc_u32 s7, s57, 0
	v_mov_b32_e32 v4, 0x1000
	v_mov_b32_e32 v5, 1
	global_atomic_add v6, v4, v5, s[6:7] offset:1024 sc0
	s_waitcnt lgkmcnt(0)
	v_mul_lo_u32 v7, v2, 8
	s_waitcnt vmcnt(0)
	v_add_u32_e32 v6, 1, v6
	v_cmp_eq_u32_e32 vcc, v6, v7
	s_cbranch_vccz .Lgb_7_waiti
	buffer_wbl2 sc1
	s_waitcnt vmcnt(0)
	v_mov_b32_e32 v4, 0x3000
	global_atomic_add v8, v4, v5, s[56:57] offset:1024 sc0
	buffer_inv sc1
	v_mul_lo_u32 v7, v3, 8
	s_waitcnt vmcnt(1)
	v_add_u32_e32 v8, 1, v8
	v_cmp_eq_u32_e32 vcc, v8, v7
	s_cbranch_vccz .Lgb_7_wait
	v_mov_b32_e32 v9, 0x2400
	global_atomic_add v9, v5, s[56:57] offset:0
	global_atomic_add v9, v5, s[56:57] offset:256
	global_atomic_add v9, v5, s[56:57] offset:512
	global_atomic_add v9, v5, s[56:57] offset:768
	global_atomic_add v9, v5, s[56:57] offset:1024
	global_atomic_add v9, v5, s[56:57] offset:1280
	global_atomic_add v9, v5, s[56:57] offset:1536
	global_atomic_add v9, v5, s[56:57] offset:1792
	global_atomic_add v9, v5, s[56:57] offset:2048
	global_atomic_add v9, v5, s[56:57] offset:2304
	global_atomic_add v9, v5, s[56:57] offset:2560
	global_atomic_add v9, v5, s[56:57] offset:2816
	global_atomic_add v9, v5, s[56:57] offset:3072
	global_atomic_add v9, v5, s[56:57] offset:3328
	global_atomic_add v9, v5, s[56:57] offset:3584
	global_atomic_add v9, v5, s[56:57] offset:3840
	s_waitcnt vmcnt(0)
	s_branch .Lgb_7_done

.LBB0_1041:
	s_cmp_gt_i32 s59, 11
	s_cselect_b64 s[4:5], -1, 0
	s_and_b64 s[0:1], s[0:1], s[4:5]
	s_andn2_b64 vcc, exec, s[0:1]
	s_cbranch_vccnz .LBB0_1095
	s_waitcnt vmcnt(0) lgkmcnt(0)
	s_barrier
	s_mov_b64 s[0:1], exec
	v_readlane_b32 s2, v249, 5
	v_readlane_b32 s3, v249, 6
	v_readlane_b32 s8, v249, 4
	s_and_b64 s[2:3], s[0:1], s[2:3]
	s_mov_b64 exec, s[2:3]
	s_cbranch_execz .Lgb_8_done
	v_mov_b32_e32 v1, 0x27e00
	ds_read2_b32 v[2:3], v1 offset1:1
	s_lshl_b32 s8, s8, 8
	s_add_u32 s6, s56, s8
	s_addc_u32 s7, s57, 0
	v_mov_b32_e32 v4, 0x1000
	v_mov_b32_e32 v5, 1
	global_atomic_add v6, v4, v5, s[6:7] offset:1024 sc0
	s_waitcnt lgkmcnt(0)
	v_mul_lo_u32 v7, v2, 9
	s_waitcnt vmcnt(0)
	v_add_u32_e32 v6, 1, v6
	v_cmp_eq_u32_e32 vcc, v6, v7
	s_cbranch_vccz .Lgb_8_waiti
	buffer_wbl2 sc1
	s_waitcnt vmcnt(0)
	v_mov_b32_e32 v4, 0x3000
	global_atomic_add v8, v4, v5, s[56:57] offset:1024 sc0
	buffer_inv sc1
	v_mul_lo_u32 v7, v3, 9
	s_waitcnt vmcnt(1)
	v_add_u32_e32 v8, 1, v8
	v_cmp_eq_u32_e32 vcc, v8, v7
	s_cbranch_vccz .Lgb_8_wait
	v_mov_b32_e32 v9, 0x2400
	global_atomic_add v9, v5, s[56:57] offset:0
	global_atomic_add v9, v5, s[56:57] offset:256
	global_atomic_add v9, v5, s[56:57] offset:512
	global_atomic_add v9, v5, s[56:57] offset:768
	global_atomic_add v9, v5, s[56:57] offset:1024
	global_atomic_add v9, v5, s[56:57] offset:1280
	global_atomic_add v9, v5, s[56:57] offset:1536
	global_atomic_add v9, v5, s[56:57] offset:1792
	global_atomic_add v9, v5, s[56:57] offset:2048
	global_atomic_add v9, v5, s[56:57] offset:2304
	global_atomic_add v9, v5, s[56:57] offset:2560
	global_atomic_add v9, v5, s[56:57] offset:2816
	global_atomic_add v9, v5, s[56:57] offset:3072
	global_atomic_add v9, v5, s[56:57] offset:3328
	global_atomic_add v9, v5, s[56:57] offset:3584
	global_atomic_add v9, v5, s[56:57] offset:3840
	s_waitcnt vmcnt(0)
	s_branch .Lgb_8_done

.LBB0_1214:
	s_cmp_gt_i32 s59, 12
	s_cselect_b64 s[4:5], -1, 0
	s_and_b64 s[6:7], s[36:37], s[4:5]
	s_andn2_b64 vcc, exec, s[6:7]
	s_cbranch_vccnz .LBB0_1268
	s_waitcnt vmcnt(0) lgkmcnt(0)
	s_barrier
	s_mov_b64 s[6:7], exec
	v_readlane_b32 s8, v249, 5
	v_readlane_b32 s9, v249, 6
	v_readlane_b32 s12, v249, 4
	s_and_b64 s[8:9], s[6:7], s[8:9]
	s_mov_b64 exec, s[8:9]
	s_cbranch_execz .Lgb_9_done
	v_mov_b32_e32 v1, 0x27e00
	ds_read2_b32 v[2:3], v1 offset1:1
	s_lshl_b32 s12, s12, 8
	s_add_u32 s10, s56, s12
	s_addc_u32 s11, s57, 0
	v_mov_b32_e32 v4, 0x1000
	v_mov_b32_e32 v5, 1
	global_atomic_add v6, v4, v5, s[10:11] offset:1024 sc0
	s_waitcnt lgkmcnt(0)
	v_mul_lo_u32 v7, v2, 10
	s_waitcnt vmcnt(0)
	v_add_u32_e32 v6, 1, v6
	v_cmp_eq_u32_e32 vcc, v6, v7
	s_cbranch_vccz .Lgb_9_waiti
	buffer_wbl2 sc1
	s_waitcnt vmcnt(0)
	v_mov_b32_e32 v4, 0x3000
	global_atomic_add v8, v4, v5, s[56:57] offset:1024 sc0
	buffer_inv sc1
	v_mul_lo_u32 v7, v3, 10
	s_waitcnt vmcnt(1)
	v_add_u32_e32 v8, 1, v8
	v_cmp_eq_u32_e32 vcc, v8, v7
	s_cbranch_vccz .Lgb_9_wait
	v_mov_b32_e32 v9, 0x2400
	global_atomic_add v9, v5, s[56:57] offset:0
	global_atomic_add v9, v5, s[56:57] offset:256
	global_atomic_add v9, v5, s[56:57] offset:512
	global_atomic_add v9, v5, s[56:57] offset:768
	global_atomic_add v9, v5, s[56:57] offset:1024
	global_atomic_add v9, v5, s[56:57] offset:1280
	global_atomic_add v9, v5, s[56:57] offset:1536
	global_atomic_add v9, v5, s[56:57] offset:1792
	global_atomic_add v9, v5, s[56:57] offset:2048
	global_atomic_add v9, v5, s[56:57] offset:2304
	global_atomic_add v9, v5, s[56:57] offset:2560
	global_atomic_add v9, v5, s[56:57] offset:2816
	global_atomic_add v9, v5, s[56:57] offset:3072
	global_atomic_add v9, v5, s[56:57] offset:3328
	global_atomic_add v9, v5, s[56:57] offset:3584
	global_atomic_add v9, v5, s[56:57] offset:3840
	s_waitcnt vmcnt(0)
	s_branch .Lgb_9_done

.LBB0_1275:
	s_cmp_gt_i32 s59, 13
	s_cselect_b64 s[4:5], -1, 0
	s_and_b64 s[6:7], s[6:7], s[4:5]
	s_andn2_b64 vcc, exec, s[6:7]
	s_cbranch_vccnz .LBB0_1329
	s_waitcnt vmcnt(0) lgkmcnt(0)
	s_barrier
	s_mov_b64 s[6:7], exec
	v_readlane_b32 s8, v249, 5
	v_readlane_b32 s9, v249, 6
	v_readlane_b32 s12, v249, 4
	s_and_b64 s[8:9], s[6:7], s[8:9]
	s_mov_b64 exec, s[8:9]
	s_cbranch_execz .Lgb_10_done
	v_mov_b32_e32 v1, 0x27e00
	ds_read2_b32 v[2:3], v1 offset1:1
	s_lshl_b32 s12, s12, 8
	s_add_u32 s10, s56, s12
	s_addc_u32 s11, s57, 0
	v_mov_b32_e32 v4, 0x1000
	v_mov_b32_e32 v5, 1
	global_atomic_add v6, v4, v5, s[10:11] offset:1024 sc0
	s_waitcnt lgkmcnt(0)
	v_mul_lo_u32 v7, v2, 11
	s_waitcnt vmcnt(0)
	v_add_u32_e32 v6, 1, v6
	v_cmp_eq_u32_e32 vcc, v6, v7
	s_cbranch_vccz .Lgb_10_waiti
	buffer_wbl2 sc1
	s_waitcnt vmcnt(0)
	v_mov_b32_e32 v4, 0x3000
	global_atomic_add v8, v4, v5, s[56:57] offset:1024 sc0
	buffer_inv sc1
	v_mul_lo_u32 v7, v3, 11
	s_waitcnt vmcnt(1)
	v_add_u32_e32 v8, 1, v8
	v_cmp_eq_u32_e32 vcc, v8, v7
	s_cbranch_vccz .Lgb_10_wait
	v_mov_b32_e32 v9, 0x2400
	global_atomic_add v9, v5, s[56:57] offset:0
	global_atomic_add v9, v5, s[56:57] offset:256
	global_atomic_add v9, v5, s[56:57] offset:512
	global_atomic_add v9, v5, s[56:57] offset:768
	global_atomic_add v9, v5, s[56:57] offset:1024
	global_atomic_add v9, v5, s[56:57] offset:1280
	global_atomic_add v9, v5, s[56:57] offset:1536
	global_atomic_add v9, v5, s[56:57] offset:1792
	global_atomic_add v9, v5, s[56:57] offset:2048
	global_atomic_add v9, v5, s[56:57] offset:2304
	global_atomic_add v9, v5, s[56:57] offset:2560
	global_atomic_add v9, v5, s[56:57] offset:2816
	global_atomic_add v9, v5, s[56:57] offset:3072
	global_atomic_add v9, v5, s[56:57] offset:3328
	global_atomic_add v9, v5, s[56:57] offset:3584
	global_atomic_add v9, v5, s[56:57] offset:3840
	s_waitcnt vmcnt(0)
	s_branch .Lgb_10_done

.LBB0_1346:
	s_cmp_lt_i32 s58, 14
	s_cselect_b64 s[2:3], -1, 0
	s_cmp_gt_i32 s59, 14
	s_cselect_b64 s[0:1], -1, 0
	s_and_b64 s[2:3], s[2:3], s[0:1]
	s_andn2_b64 vcc, exec, s[2:3]
	s_cbranch_vccnz .LBB0_1400
	s_waitcnt vmcnt(0) lgkmcnt(0)
	s_barrier
	s_mov_b64 s[2:3], exec
	v_readlane_b32 s4, v249, 5
	v_readlane_b32 s5, v249, 6
	v_readlane_b32 s8, v249, 4
	s_and_b64 s[4:5], s[2:3], s[4:5]
	s_mov_b64 exec, s[4:5]
	s_cbranch_execz .Lgb_11_done
	v_mov_b32_e32 v1, 0x27e00
	ds_read2_b32 v[2:3], v1 offset1:1
	s_lshl_b32 s8, s8, 8
	s_add_u32 s6, s56, s8
	s_addc_u32 s7, s57, 0
	v_mov_b32_e32 v4, 0x1000
	v_mov_b32_e32 v5, 1
	global_atomic_add v6, v4, v5, s[6:7] offset:1024 sc0
	s_waitcnt lgkmcnt(0)
	v_mul_lo_u32 v7, v2, 12
	s_waitcnt vmcnt(0)
	v_add_u32_e32 v6, 1, v6
	v_cmp_eq_u32_e32 vcc, v6, v7
	s_cbranch_vccz .Lgb_11_waiti
	buffer_wbl2 sc1
	s_waitcnt vmcnt(0)
	v_mov_b32_e32 v4, 0x3000
	global_atomic_add v8, v4, v5, s[56:57] offset:1024 sc0
	buffer_inv sc1
	v_mul_lo_u32 v7, v3, 12
	s_waitcnt vmcnt(1)
	v_add_u32_e32 v8, 1, v8
	v_cmp_eq_u32_e32 vcc, v8, v7
	s_cbranch_vccz .Lgb_11_wait
	v_mov_b32_e32 v9, 0x2400
	global_atomic_add v9, v5, s[56:57] offset:0
	global_atomic_add v9, v5, s[56:57] offset:256
	global_atomic_add v9, v5, s[56:57] offset:512
	global_atomic_add v9, v5, s[56:57] offset:768
	global_atomic_add v9, v5, s[56:57] offset:1024
	global_atomic_add v9, v5, s[56:57] offset:1280
	global_atomic_add v9, v5, s[56:57] offset:1536
	global_atomic_add v9, v5, s[56:57] offset:1792
	global_atomic_add v9, v5, s[56:57] offset:2048
	global_atomic_add v9, v5, s[56:57] offset:2304
	global_atomic_add v9, v5, s[56:57] offset:2560
	global_atomic_add v9, v5, s[56:57] offset:2816
	global_atomic_add v9, v5, s[56:57] offset:3072
	global_atomic_add v9, v5, s[56:57] offset:3328
	global_atomic_add v9, v5, s[56:57] offset:3584
	global_atomic_add v9, v5, s[56:57] offset:3840
	s_waitcnt vmcnt(0)
	s_branch .Lgb_11_done

.LBB0_1555:
	s_cmp_gt_i32 s59, 16
	s_cselect_b64 s[4:5], -1, 0
	s_and_b64 s[0:1], s[10:11], s[4:5]
	s_andn2_b64 vcc, exec, s[0:1]
	s_cbranch_vccnz .LBB0_1609
	s_waitcnt vmcnt(0) lgkmcnt(0)
	s_barrier
	s_mov_b64 s[0:1], exec
	v_readlane_b32 s2, v249, 5
	v_readlane_b32 s3, v249, 6
	v_readlane_b32 s8, v249, 4
	s_and_b64 s[2:3], s[0:1], s[2:3]
	s_mov_b64 exec, s[2:3]
	s_cbranch_execz .Lgb_12_done
	v_mov_b32_e32 v1, 0x27e00
	ds_read2_b32 v[2:3], v1 offset1:1
	s_lshl_b32 s8, s8, 8
	s_add_u32 s6, s56, s8
	s_addc_u32 s7, s57, 0
	v_mov_b32_e32 v4, 0x1000
	v_mov_b32_e32 v5, 1
	global_atomic_add v6, v4, v5, s[6:7] offset:1024 sc0
	s_waitcnt lgkmcnt(0)
	v_mul_lo_u32 v7, v2, 13
	s_waitcnt vmcnt(0)
	v_add_u32_e32 v6, 1, v6
	v_cmp_eq_u32_e32 vcc, v6, v7
	s_cbranch_vccz .Lgb_12_waiti
	buffer_wbl2 sc1
	s_waitcnt vmcnt(0)
	v_mov_b32_e32 v4, 0x3000
	global_atomic_add v8, v4, v5, s[56:57] offset:1024 sc0
	buffer_inv sc1
	v_mul_lo_u32 v7, v3, 13
	s_waitcnt vmcnt(1)
	v_add_u32_e32 v8, 1, v8
	v_cmp_eq_u32_e32 vcc, v8, v7
	s_cbranch_vccz .Lgb_12_wait
	v_mov_b32_e32 v9, 0x2400
	global_atomic_add v9, v5, s[56:57] offset:0
	global_atomic_add v9, v5, s[56:57] offset:256
	global_atomic_add v9, v5, s[56:57] offset:512
	global_atomic_add v9, v5, s[56:57] offset:768
	global_atomic_add v9, v5, s[56:57] offset:1024
	global_atomic_add v9, v5, s[56:57] offset:1280
	global_atomic_add v9, v5, s[56:57] offset:1536
	global_atomic_add v9, v5, s[56:57] offset:1792
	global_atomic_add v9, v5, s[56:57] offset:2048
	global_atomic_add v9, v5, s[56:57] offset:2304
	global_atomic_add v9, v5, s[56:57] offset:2560
	global_atomic_add v9, v5, s[56:57] offset:2816
	global_atomic_add v9, v5, s[56:57] offset:3072
	global_atomic_add v9, v5, s[56:57] offset:3328
	global_atomic_add v9, v5, s[56:57] offset:3584
	global_atomic_add v9, v5, s[56:57] offset:3840
	s_waitcnt vmcnt(0)
	s_branch .Lgb_12_done

.LBB0_1626:
	s_cmp_gt_i32 s59, 17
	s_cselect_b64 s[4:5], -1, 0
	s_and_b64 s[0:1], s[0:1], s[4:5]
	s_andn2_b64 vcc, exec, s[0:1]
	s_cbranch_vccnz .LBB0_1680
	s_waitcnt vmcnt(0) lgkmcnt(0)
	s_barrier
	s_mov_b64 s[0:1], exec
	v_readlane_b32 s2, v249, 5
	v_readlane_b32 s3, v249, 6
	v_readlane_b32 s8, v249, 4
	s_and_b64 s[2:3], s[0:1], s[2:3]
	s_mov_b64 exec, s[2:3]
	s_cbranch_execz .Lgb_13_done
	v_mov_b32_e32 v1, 0x27e00
	ds_read2_b32 v[2:3], v1 offset1:1
	s_lshl_b32 s8, s8, 8
	s_add_u32 s6, s56, s8
	s_addc_u32 s7, s57, 0
	v_mov_b32_e32 v4, 0x1000
	v_mov_b32_e32 v5, 1
	global_atomic_add v6, v4, v5, s[6:7] offset:1024 sc0
	s_waitcnt lgkmcnt(0)
	v_mul_lo_u32 v7, v2, 14
	s_waitcnt vmcnt(0)
	v_add_u32_e32 v6, 1, v6
	v_cmp_eq_u32_e32 vcc, v6, v7
	s_cbranch_vccz .Lgb_13_waiti
	buffer_wbl2 sc1
	s_waitcnt vmcnt(0)
	v_mov_b32_e32 v4, 0x3000
	global_atomic_add v8, v4, v5, s[56:57] offset:1024 sc0
	buffer_inv sc1
	v_mul_lo_u32 v7, v3, 14
	s_waitcnt vmcnt(1)
	v_add_u32_e32 v8, 1, v8
	v_cmp_eq_u32_e32 vcc, v8, v7
	s_cbranch_vccz .Lgb_13_wait
	v_mov_b32_e32 v9, 0x2400
	global_atomic_add v9, v5, s[56:57] offset:0
	global_atomic_add v9, v5, s[56:57] offset:256
	global_atomic_add v9, v5, s[56:57] offset:512
	global_atomic_add v9, v5, s[56:57] offset:768
	global_atomic_add v9, v5, s[56:57] offset:1024
	global_atomic_add v9, v5, s[56:57] offset:1280
	global_atomic_add v9, v5, s[56:57] offset:1536
	global_atomic_add v9, v5, s[56:57] offset:1792
	global_atomic_add v9, v5, s[56:57] offset:2048
	global_atomic_add v9, v5, s[56:57] offset:2304
	global_atomic_add v9, v5, s[56:57] offset:2560
	global_atomic_add v9, v5, s[56:57] offset:2816
	global_atomic_add v9, v5, s[56:57] offset:3072
	global_atomic_add v9, v5, s[56:57] offset:3328
	global_atomic_add v9, v5, s[56:57] offset:3584
	global_atomic_add v9, v5, s[56:57] offset:3840
	s_waitcnt vmcnt(0)
	s_branch .Lgb_13_done
